# MIX phase: workgroups with blockIdx bit 2 set run attention before the FFT unit (complementary phase order across XCDs)
# speedup vs baseline: 1.0030x; 1.0030x over previous
; #define GEMMCALL if (0)
; #define FRESH_TID() asm volatile("" : "+v"(tid))
; __global__ void __launch_bounds__(NTHREADS, 2) mega(Params p) {
;     ...
;             for (int rep = 0; rep < REP_FOUR; ++rep) { FRESH_TID(); fft_phase(p, lds, tid); }
;             if (l == 0) {
;                 pg8::Gemm g{(const bf16_t*)(ws + WS_CTC), (const bf16_t*)(ws + WS_ZTC), 256, 2048, 512}; pg8::StaticOrder S; S.init(256, 2048, G, (int)blockIdx.x);
;                 EpiStore<0> E{MIX + (size_t)MX * KOUT + 512, KOUT, (size_t)256 * KOUT};
;                 GEMMCALL pg8::gemm_phase<EpiStore<0>, pg8::StaticOrder, true, true>(lds, g, S, E);
;             }
;             __syncthreads();
;             for (int rep = 0; rep < REP_ATTN; ++rep) { FRESH_TID(); attn_phase(p, l, lds, tid); }
.LBB0_452:
	s_or_b64 exec, exec, s[0:1]
	v_readlane_b32 s0, v254, 56
	v_readlane_b32 s1, v254, 57
	s_andn2_b64 vcc, exec, s[0:1]
	s_waitcnt lgkmcnt(0)
	s_barrier
	s_mov_b32 s68, 0
	s_bitcmp1_b32 s2, 2
	s_cbranch_scc0 .Lmix_norm
	s_mov_b32 s68, 1
	s_branch .LBB0_455

; #define LAS __attribute__((address_space(3)))
; #define GAS __attribute__((address_space(1)))
; __device__ __forceinline__ void fft_phase(const Params& p, LAS unsigned char* lds, int tid) {
;     unsigned char* ws = p.ws;
;     const bf16_t* ZT = (const bf16_t*)(ws + WS_ZT); bf16_t* MIX = (bf16_t*)(ws + WS_MIX);
;     const bf16_t* FA = (const bf16_t*)(ws + WS_FA); const bf16_t* FB = (const bf16_t*)(ws + WS_FB); const float* TW = (const float*)(ws + WS_TW);
;     LAS unsigned short* Z = (LAS unsigned short*)lds;
;     const int lane = tid & 63, w = tid >> 6, r32 = lane & 31, hi = lane >> 5;
;     for (int u = blockIdx.x; u < 256; u += gridDim.x) {
;         const int b = u >> 5, g = (u >> 3) & 3, cb = u & 7;
;         {
;             u32x4 v[16];
; #pragma unroll
;             for (int j = 0; j < 16; ++j) v[j] = *(const u32x4*)(ZT + ((size_t)((j >> 3) * 2048 + b * 256 + g * 64 + cb * 8 + (j & 7))) * 4096 + tid * 8);
; #pragma unroll
;             for (int j = 0; j < 16; ++j) *(LAS u32x4*)(Z + j * 4096 + tid * 8) = v[j];
;         }
;         __syncthreads();
;         LAS unsigned short* Zr = Z + w * 4096; LAS unsigned short* Zi = Z + (8 + w) * 4096;
;         for (int nh = 0; nh < 2; ++nh) {
;             const int n2 = nh * 32 + r32;
;             int two = (n2 * 64 + 4 * hi) * 2; asm volatile("" : "+v"(two));
;             const GAS float* twp = (const GAS float*)TW + two;
;             f32x4 tw0[2][4], tw1[2][4];
; #pragma unroll
;             for (int rg = 0; rg < 4; ++rg) { tw0[0][rg] = *(const GAS f32x4*)(twp + (8 * rg) * 2); tw1[0][rg] = *(const GAS f32x4*)(twp + (8 * rg) * 2 + 4); }
;             bf16x8 bfA[8];
; #pragma unroll
;             for (int s = 0; s < 8; ++s) {
;                 const LAS unsigned short* q = Z + ((s >> 2) * 8 + w) * 4096 + (16 * (s & 3) + 8 * hi) * 64 + n2;
.Lmix_fft:
	v_lshlrev_b32_e32 v0, 3, v144
	v_readlane_b32 s0, v254, 50
	v_ashrrev_i32_e32 v5, 6, v144
	v_ashrrev_i32_e32 v1, 31, v0
	v_readlane_b32 s1, v254, 51
	v_bfe_u32 v3, v144, 5, 1
	v_and_b32_e32 v4, 31, v144
	v_lshl_add_u64 v[124:125], v[0:1], 1, s[0:1]
	v_lshl_add_u32 v0, v5, 13, 0
	v_add_u32_e32 v1, 0x10000, v0
	v_lshlrev_b32_e32 v6, 8, v3
	v_lshlrev_b32_e32 v8, 10, v3
	v_lshlrev_b32_e32 v12, 1, v4
	v_add3_u32 v130, v0, v8, v12
	v_add3_u32 v131, v1, v8, v12
	v_or_b32_e32 v8, v6, v4
	v_lshlrev_b32_e32 v8, 1, v8
	v_add_u32_e32 v132, v0, v8
	v_add_u32_e32 v133, v1, v8
	v_or_b32_e32 v8, 64, v6
	v_bitop3_b32 v12, v144, 8, 31 bitop3:0x6c
	v_or_b32_e32 v13, v8, v12
	v_bitop3_b32 v14, v6, v4, 8 bitop3:0xf6
	v_lshl_add_u32 v134, v14, 1, v0
	v_lshl_add_u32 v135, v13, 1, v1
	v_or_b32_e32 v13, 0x80, v6
	v_bitop3_b32 v14, v144, 16, 31 bitop3:0x6c
	v_or_b32_e32 v15, v13, v14
	v_bitop3_b32 v16, v6, v4, 16 bitop3:0xf6
	v_lshl_add_u32 v136, v16, 1, v0
	v_lshl_add_u32 v137, v15, 1, v1
	v_or_b32_e32 v15, 0xc0, v6
	v_bitop3_b32 v16, v144, 24, 31 bitop3:0x6c
	v_or_b32_e32 v17, v15, v16
	v_bitop3_b32 v18, v6, v4, 24 bitop3:0xf6
	v_lshl_add_u32 v139, v17, 1, v1
	v_or_b32_e32 v17, 0x200, v6
	v_lshl_add_u32 v138, v18, 1, v0
	v_or_b32_e32 v18, v17, v4
	v_lshl_add_u32 v140, v18, 1, v1
	v_or_b32_e32 v18, 0x240, v6
	v_or_b32_e32 v19, v18, v12
	v_lshl_add_u32 v141, v19, 1, v1
	v_or_b32_e32 v19, 0x280, v6
	v_or_b32_e32 v20, v19, v14
	v_lshl_add_u32 v142, v20, 1, v1
	v_or_b32_e32 v20, 0x2c0, v6
	v_or_b32_e32 v21, v20, v16
	v_lshl_add_u32 v143, v21, 1, v1
	v_or_b32_e32 v21, 0x400, v6
	v_or_b32_e32 v22, v21, v4
	v_lshl_add_u32 v145, v22, 1, v1
	v_or_b32_e32 v22, 0x440, v6
	v_or_b32_e32 v23, v22, v12
	v_lshl_add_u32 v146, v23, 1, v1
	v_or_b32_e32 v23, 0x480, v6
	v_or_b32_e32 v24, v23, v14
	v_lshl_add_u32 v147, v24, 1, v1
	v_or_b32_e32 v24, 0x4c0, v6
	v_or_b32_e32 v25, v24, v16
	v_lshl_add_u32 v148, v25, 1, v1
	v_or_b32_e32 v25, 0x600, v6
	v_or_b32_e32 v26, v25, v4
	v_lshl_add_u32 v149, v26, 1, v1
	v_or_b32_e32 v26, 0x640, v6
	v_or_b32_e32 v27, v26, v12
	v_lshl_add_u32 v150, v27, 1, v1
	v_or_b32_e32 v27, 0x680, v6
	v_or_b32_e32 v28, v27, v14
	v_lshl_add_u32 v151, v28, 1, v1
	v_or_b32_e32 v28, 0x6c0, v6
	v_or_b32_e32 v29, v28, v16
	v_lshl_add_u32 v152, v29, 1, v1
	v_or_b32_e32 v29, 0x800, v6
	v_or_b32_e32 v30, v29, v4
	v_lshl_add_u32 v153, v30, 1, v1
	v_or_b32_e32 v30, 0x840, v6
	v_or_b32_e32 v31, v30, v12
	v_lshl_add_u32 v154, v31, 1, v1
	v_or_b32_e32 v31, 0x880, v6
	v_or_b32_e32 v32, v31, v14
	v_lshl_add_u32 v155, v32, 1, v1
	v_or_b32_e32 v32, 0x8c0, v6
	v_or_b32_e32 v33, v32, v16
	v_lshl_add_u32 v156, v33, 1, v1
	v_or_b32_e32 v33, 0xa00, v6
	v_or_b32_e32 v34, v33, v4
	v_lshl_add_u32 v157, v34, 1, v1
	v_or_b32_e32 v34, 0xa40, v6
	v_or_b32_e32 v35, v34, v12
	v_lshl_add_u32 v158, v35, 1, v1
	v_or_b32_e32 v35, 0xa80, v6
	v_or_b32_e32 v36, v35, v14
	v_lshl_add_u32 v159, v36, 1, v1
	v_or_b32_e32 v36, 0xac0, v6
	v_or_b32_e32 v37, v36, v16
	v_lshl_add_u32 v160, v37, 1, v1
	v_or_b32_e32 v37, 0xc00, v6
	v_or_b32_e32 v38, v37, v4
	v_lshl_add_u32 v161, v38, 1, v1
	v_or_b32_e32 v38, 0xc40, v6
	v_or_b32_e32 v39, v38, v12
	v_lshl_add_u32 v162, v39, 1, v1
	v_or_b32_e32 v39, 0xc80, v6
	v_or_b32_e32 v40, v39, v14
	v_lshl_add_u32 v163, v40, 1, v1
	v_or_b32_e32 v40, 0xcc0, v6
	v_or_b32_e32 v41, v40, v16
	v_lshl_add_u32 v164, v41, 1, v1
	v_or_b32_e32 v41, 0xe00, v6
	v_or_b32_e32 v42, v41, v4
	v_lshl_add_u32 v165, v42, 1, v1
	v_or_b32_e32 v42, 0xe40, v6
	v_or_b32_e32 v12, v42, v12
	v_lshl_add_u32 v166, v12, 1, v1
	v_or_b32_e32 v12, 0xe80, v6
	v_or_b32_e32 v14, v12, v14
	v_lshl_add_u32 v167, v14, 1, v1
	v_or_b32_e32 v14, 0xec0, v6
	v_or_b32_e32 v16, v14, v16
	v_lshlrev_b32_e32 v7, 3, v3
	v_lshlrev_b32_e32 v9, 7, v4
	v_lshl_add_u32 v168, v16, 1, v1
; __device__ __forceinline__ void fft_phase(const Params& p, LAS unsigned char* lds, int tid) {
;     ...
;     const int lane = tid & 63, w = tid >> 6, r32 = lane & 31, hi = lane >> 5;
;     for (int u = blockIdx.x; u < 256; u += gridDim.x) {
;         const int b = u >> 5, g = (u >> 3) & 3, cb = u & 7;
;         {
;             u32x4 v[16];
; #pragma unroll
;             for (int j = 0; j < 16; ++j) v[j] = *(const u32x4*)(ZT + ((size_t)((j >> 3) * 2048 + b * 256 + g * 64 + cb * 8 + (j & 7))) * 4096 + tid * 8);
; #pragma unroll
;             for (int j = 0; j < 16; ++j) *(LAS u32x4*)(Z + j * 4096 + tid * 8) = v[j];
;         }
;         __syncthreads();
;         LAS unsigned short* Zr = Z + w * 4096; LAS unsigned short* Zi = Z + (8 + w) * 4096;
;         for (int nh = 0; nh < 2; ++nh) {
;             const int n2 = nh * 32 + r32;
;             int two = (n2 * 64 + 4 * hi) * 2; asm volatile("" : "+v"(two));
;             const GAS float* twp = (const GAS float*)TW + two;
;             f32x4 tw0[2][4], tw1[2][4];
; #pragma unroll
;             for (int rg = 0; rg < 4; ++rg) { tw0[0][rg] = *(const GAS f32x4*)(twp + (8 * rg) * 2); tw1[0][rg] = *(const GAS f32x4*)(twp + (8 * rg) * 2 + 4); }
;             bf16x8 bfA[8];
; #pragma unroll
;             for (int s = 0; s < 8; ++s) {
;                 const LAS unsigned short* q = Z + ((s >> 2) * 8 + w) * 4096 + (16 * (s & 3) + 8 * hi) * 64 + n2;
;                 u32x4 t;
;                 t.x = (unsigned)q[0] | ((unsigned)q[64] << 16); t.y = (unsigned)q[128] | ((unsigned)q[192] << 16);
;                 t.z = (unsigned)q[256] | ((unsigned)q[320] << 16); t.w = (unsigned)q[384] | ((unsigned)q[448] << 16);
;                 bfA[s] = __builtin_bit_cast(bf16x8, t);
;             }
;             f32x16 acc[4];
;             int fao = r32 * 128 + 8 * hi; asm volatile("" : "+v"(fao));
;             const GAS bf16_t* fap = (const GAS bf16_t*)FA + fao;
; #pragma unroll
;             for (int mt = 0; mt < 4; ++mt) {
; #pragma unroll
;                 for (int e = 0; e < 16; ++e) acc[mt][e] = 0.f;
; #pragma unroll
;                 for (int s = 0; s < 8; ++s) {
;                     const bf16x8 a = *(const GAS bf16x8*)(fap + mt * 32 * 128 + 16 * s);
;                     acc[mt] = __builtin_amdgcn_mfma_f32_32x32x16_bf16(a, bfA[s], acc[mt], 0, 0, 0);
;                 }
;                 asm volatile("" ::: "memory");
;             }
	v_or_b32_e32 v16, 32, v4
	v_or_b32_e32 v129, v7, v9
	v_and_b32_e32 v10, 7, v144
	v_lshl_or_b32 v169, v16, 7, v7
	v_bitop3_b32 v7, v4, 56, 32 bitop3:0xc8
	v_or_b32_e32 v16, v7, v10
	v_or_b32_e32 v43, v16, v6
	v_lshlrev_b32_e32 v43, 1, v43
	v_bitop3_b32 v44, v16, v6, 8 bitop3:0xde
	v_add_u32_e32 v170, v0, v43
	v_add_u32_e32 v171, v1, v43
	v_bitop3_b32 v43, v7, 8, v10 bitop3:0x36
	v_lshl_add_u32 v172, v44, 1, v0
	v_bitop3_b32 v44, v16, v6, 16 bitop3:0xde
	v_bitop3_b32 v6, v16, v6, 24 bitop3:0xde
	v_or_b32_e32 v8, v43, v8
	v_lshl_add_u32 v176, v6, 1, v0
	v_or_b32_e32 v6, v16, v17
	v_lshl_add_u32 v173, v8, 1, v1
	v_bitop3_b32 v8, v7, 16, v10 bitop3:0x36
	v_lshl_add_u32 v178, v6, 1, v1
	v_or_b32_e32 v6, v43, v18
	v_bitop3_b32 v7, v7, 24, v10 bitop3:0x36
	v_lshl_add_u32 v179, v6, 1, v1
	v_or_b32_e32 v6, v8, v19
	v_lshl_add_u32 v180, v6, 1, v1
	v_or_b32_e32 v6, v7, v20
	v_lshl_add_u32 v181, v6, 1, v1
	v_or_b32_e32 v6, v16, v21
	v_lshl_add_u32 v182, v6, 1, v1
	v_or_b32_e32 v6, v43, v22
	v_lshl_add_u32 v183, v6, 1, v1
	v_or_b32_e32 v6, v8, v23
	v_lshl_add_u32 v184, v6, 1, v1
	v_or_b32_e32 v6, v7, v24
	v_lshl_add_u32 v185, v6, 1, v1
	v_or_b32_e32 v6, v16, v25
	v_lshl_add_u32 v186, v6, 1, v1
	v_or_b32_e32 v6, v43, v26
	v_lshl_add_u32 v192, v6, 1, v1
	v_or_b32_e32 v6, v8, v27
	v_lshl_add_u32 v193, v6, 1, v1
	v_or_b32_e32 v6, v7, v28
	v_lshl_add_u32 v194, v6, 1, v1
	v_or_b32_e32 v6, v16, v29
	v_lshl_add_u32 v195, v6, 1, v1
	v_or_b32_e32 v6, v43, v30
	v_lshl_add_u32 v196, v6, 1, v1
	v_or_b32_e32 v6, v8, v31
	v_lshl_add_u32 v197, v6, 1, v1
	v_or_b32_e32 v6, v7, v32
	v_lshl_add_u32 v198, v6, 1, v1
	v_or_b32_e32 v6, v16, v33
	v_lshl_add_u32 v199, v6, 1, v1
	v_or_b32_e32 v6, v43, v34
	v_lshl_add_u32 v200, v6, 1, v1
	v_or_b32_e32 v6, v8, v35
	v_lshl_add_u32 v201, v6, 1, v1
	v_or_b32_e32 v6, v7, v36
	v_lshl_add_u32 v202, v6, 1, v1
	v_or_b32_e32 v6, v16, v37
	v_lshl_add_u32 v203, v6, 1, v1
	v_or_b32_e32 v6, v43, v38
	v_lshl_add_u32 v204, v6, 1, v1
	v_or_b32_e32 v6, v8, v39
	v_lshrrev_b32_e32 v2, 5, v144
	v_and_b32_e32 v11, 3, v144
	v_lshl_add_u32 v205, v6, 1, v1
	v_or_b32_e32 v6, v7, v40
	v_lshl_add_u32 v174, v44, 1, v0
	v_lshl_add_u32 v206, v6, 1, v1
	v_or_b32_e32 v6, v16, v41
	v_add_u32_e32 v211, v0, v9
	v_bitop3_b32 v0, v2, v11, 1 bitop3:0x6c
	v_lshl_add_u32 v207, v6, 1, v1
	v_or_b32_e32 v6, v43, v42
	v_lshlrev_b32_e32 v212, 4, v0
	v_bitop3_b32 v0, v3, v11, 2 bitop3:0x36
	v_lshl_add_u32 v208, v6, 1, v1
	v_or_b32_e32 v6, v8, v12
	v_lshlrev_b32_e32 v213, 4, v0
	v_bitop3_b32 v0, v3, v11, 4 bitop3:0x36
	v_or_b32_e32 v13, v8, v13
	v_or_b32_e32 v10, v7, v15
	v_lshl_add_u32 v209, v6, 1, v1
	v_or_b32_e32 v6, v7, v14
	v_lshlrev_b32_e32 v214, 4, v0
	v_bitop3_b32 v0, v3, v11, 6 bitop3:0x36
	v_lshl_add_u32 v5, v5, 1, 0
	v_lshl_add_u32 v175, v13, 1, v1
	v_lshl_add_u32 v177, v10, 1, v1
	v_lshl_add_u32 v210, v6, 1, v1
	v_lshlrev_b32_e32 v215, 4, v0
	v_lshlrev_b32_e32 v0, 12, v3
	v_lshlrev_b32_e32 v1, 4, v4
	v_add_u32_e32 v219, 0x200, v144
	v_add_u32_e32 v234, 0x400, v144
	v_add_u32_e32 v235, 0x600, v144
	v_add_u32_e32 v236, 0x800, v144
	v_add_u32_e32 v237, 0xa00, v144
	v_add_u32_e32 v238, 0xc00, v144
	v_add_u32_e32 v239, 0xe00, v144
	v_add3_u32 v218, v5, v0, v1
	v_lshlrev_b32_e32 v0, 4, v219
	v_lshlrev_b32_e32 v1, 4, v234
	v_lshlrev_b32_e32 v2, 4, v235
	v_lshlrev_b32_e32 v3, 4, v236
	v_lshlrev_b32_e32 v4, 4, v237
	v_lshlrev_b32_e32 v5, 4, v238
	v_lshlrev_b32_e32 v6, 4, v239
	v_lshl_add_u32 v128, v144, 4, 0
	v_add_u32_e32 v216, 0x10000, v211
	v_add_u32_e32 v217, 0x11000, v211
	v_add_u32_e32 v240, 0, v0
	v_add_u32_e32 v241, 0, v1
	v_add_u32_e32 v242, 0, v2
	v_add_u32_e32 v243, 0, v3
	v_add_u32_e32 v244, 0, v4
	v_add_u32_e32 v245, 0, v5
	v_add_u32_e32 v246, 0, v6
	v_readlane_b32 s4, v252, 29
	s_mov_b32 s5, s2

; #define PG8_WAIT_V(n) asm volatile("s_waitcnt vmcnt(" #n ")" ::: "memory")
; #define GEMMCALL if (0)
; template <class Epi, class Sched, bool ALIGN_EPI = false, bool SP2 = false>
; __device__ __forceinline__ void gemm_phase(PG8_LAS unsigned char* lds, const Gemm g, const Sched& S, const Epi& E) {
;     int tid_ = threadIdx.x; asm volatile("" : "+v"(tid_)); const int tid = tid_, wid = __builtin_amdgcn_readfirstlane(tid >> 6), lane = tid & 63, wr = wid >> 2, wc = wid & 3, fr = lane & 15, fq = lane >> 4;
;     const int K = g.K, nt = K / BK, LD = g.ld ? g.ld : g.K;
;     unsigned voffA[2], voffB[2];
; #pragma unroll
;     for (int i = 0; i < 2; ++i) { int R, C; stage_rc(tid * 16 + i * 8192, R, C); const int Rb = Epi::PERM ? ((R & ~31) + perm32(R & 31)) : R;
;         voffA[i] = (unsigned)(R * LD + C) * 2u; voffB[i] = (unsigned)(Rb * LD + C) * 2u; }
;     const size_t kstep = (size_t)(BK * 2);
;     const size_t hstep = (size_t)HALF * LD * 2;
;     const size_t tstep = 2 * hstep;
;     const unsigned ldsw = (unsigned)wid * 1024u;
;     const int aoff = lds_byte(wr * 64 + fr, fq * 8), boff = lds_byte(wc * 32 + fr, fq * 8);
;     ...
;     Unit cur, nxt; int ui = 0;
;     if (!S.next(0, cur)) return;
;     f32x4 acc[2][2][4][2];
; #pragma unroll
;     for (int a = 0; a < 2; ++a)
; #pragma unroll
;         for (int b = 0; b < 2; ++b)
; #pragma unroll
;             for (int m = 0; m < 4; ++m)
; #pragma unroll
;                 for (int n = 0; n < 2; ++n) acc[a][b][m][n] = (f32x4){0.f, 0.f, 0.f, 0.f};
;     bf16x8 At[4][2], B0[2][2], B1[2][2];
;     const char* cA = (const char*)g.A + (size_t)cur.pm * tstep; const char* cB = (const char*)g.Bt + (size_t)cur.pn * tstep;
;     S.a_ready(cur);
;     if constexpr (SP2) {
;         PG8_STAGE(PG8_SB(0, 0), cB, voffB); PG8_STAGE(PG8_SB(0, 1), cB + hstep, voffB); PG8_STAGE(PG8_SA(0, 0), cA, voffA); PG8_STAGE(PG8_SA(0, 1), cA + hstep, voffA);
;         if (wr == 1) PG8_BAR;
;         PG8_WAIT_V(2); PG8_BAR;
; __global__ void __launch_bounds__(NTHREADS, 2) mega(Params p) {
;     ...
;                 pg8::Gemm g{(const bf16_t*)(ws + WS_CTC), (const bf16_t*)(ws + WS_ZTC), 256, 2048, 512}; pg8::StaticOrder S; S.init(256, 2048, G, (int)blockIdx.x);
;                 EpiStore<0> E{MIX + (size_t)MX * KOUT + 512, KOUT, (size_t)256 * KOUT};
;                 GEMMCALL pg8::gemm_phase<EpiStore<0>, pg8::StaticOrder, true, true>(lds, g, S, E);
.LBB0_455:
	s_cmp_eq_u32 s68, 2
	s_cbranch_scc1 .Lmix_done
	s_andn2_b64 vcc, exec, s[64:65]
	s_movk_i32 s6, 0x200
	v_readlane_b32 s34, v254, 63
	v_readlane_b32 s35, v255, 0
	s_cbranch_vccnz .LBB0_473
	v_readlane_b32 s0, v254, 60
	v_mov_b32_e32 v1, v220
	v_readlane_b32 s1, v254, 61
	s_andn2_b64 vcc, exec, s[0:1]
	v_readfirstlane_b32 s4, v1
	s_cbranch_vccnz .LBB0_472
	v_lshlrev_b32_e32 v5, 4, v1
	v_add_u32_e32 v2, 0x2000, v5
	v_ashrrev_i32_e32 v0, 31, v2
	v_lshrrev_b32_e32 v0, 22, v0
	v_add_u32_e32 v0, v2, v0
	v_ashrrev_i32_e32 v0, 10, v0
	v_lshlrev_b32_e32 v3, 5, v0
	v_and_b32_e32 v4, 32, v3
	v_mul_i32_i24_e32 v3, 0x400, v0
	v_sub_u32_e32 v2, v2, v3
	v_lshrrev_b32_e32 v3, 4, v2
	v_bitop3_b32 v3, v3, v2, 32 bitop3:0x6c
	v_ashrrev_i32_e32 v2, 31, v3
	v_lshrrev_b32_e32 v2, 26, v2
	v_add_u32_e32 v6, v3, v2
	v_ashrrev_i32_e32 v2, 6, v6
	v_and_b32_e32 v6, 0xc0, v6
	v_sub_u32_e32 v3, v3, v6
	v_lshlrev_b32_e32 v6, 3, v0
	v_and_b32_e32 v6, -16, v6
	v_add_u32_e32 v6, v2, v6
	v_ashrrev_i16_sdwa v3, v222, sext(v3) dst_sel:DWORD dst_unused:UNUSED_PAD src0_sel:DWORD src1_sel:BYTE_0
	v_and_b32_e32 v7, 3, v2
	s_mov_b32 s0, 0x3fffe0
	v_lshrrev_b32_e32 v8, 2, v6
	v_lshlrev_b32_e32 v9, 1, v6
	v_bfe_i32 v3, v3, 0, 16
	v_and_or_b32 v7, v6, s0, v7
	v_and_b32_e32 v8, 4, v8
	v_and_b32_e32 v9, 24, v9
	v_or3_b32 v7, v7, v8, v9
	v_add_lshl_u32 v4, v4, v3, 1
	v_lshl_add_u32 v128, v7, 10, v4
	v_lshl_add_u32 v130, v6, 10, v4
	v_ashrrev_i32_e32 v4, 31, v1
	v_lshrrev_b32_e32 v4, 26, v4
	v_add_u32_e32 v4, v1, v4
	v_ashrrev_i32_e32 v4, 6, v4
	v_lshlrev_b32_e32 v6, 5, v4
	v_and_b32_e32 v7, 32, v6
	v_bfe_i32 v6, v1, 27, 1
	v_lshrrev_b32_e32 v6, 22, v6
	v_add_u32_e32 v6, v5, v6
	v_and_b32_e32 v6, 0xfffffc00, v6
	v_sub_u32_e32 v5, v5, v6
	v_lshrrev_b32_e32 v6, 4, v5
	v_bitop3_b32 v6, v6, v5, 32 bitop3:0x6c
	v_ashrrev_i32_e32 v5, 31, v6
	v_lshrrev_b32_e32 v5, 26, v5
	v_add_u32_e32 v8, v6, v5
	v_ashrrev_i32_e32 v5, 6, v8
	v_and_b32_e32 v8, 0xc0, v8
	v_sub_u32_e32 v6, v6, v8
	v_lshlrev_b32_e32 v8, 3, v4
	v_and_b32_e32 v8, -16, v8
	v_add_u32_e32 v8, v5, v8
	s_ashr_i32 s5, s4, 6
	v_ashrrev_i16_sdwa v6, v222, sext(v6) dst_sel:DWORD dst_unused:UNUSED_PAD src0_sel:DWORD src1_sel:BYTE_0
	v_and_b32_e32 v9, 3, v5
	v_lshrrev_b32_e32 v10, 2, v8
	v_lshlrev_b32_e32 v11, 1, v8
	s_lshl_b32 s28, s5, 10
	v_bfe_i32 v6, v6, 0, 16
	v_and_or_b32 v9, v8, s0, v9
	v_and_b32_e32 v10, 4, v10
	v_and_b32_e32 v11, 24, v11
	v_or3_b32 v9, v9, v10, v11
	v_add_lshl_u32 v7, v7, v6, 1
	s_add_i32 s29, s28, 0
	v_readlane_b32 s0, v255, 51
	v_lshl_add_u32 v186, v9, 10, v7
	s_add_i32 m0, s29, 0x10000
	v_readlane_b32 s1, v255, 52
	v_lshl_add_u32 v132, v8, 10, v7
	s_add_i32 s30, s29, 0x2000
	s_add_i32 s31, s29, 0x4000
	s_add_i32 s34, s29, 0x6000
	s_ashr_i32 s6, s4, 8
	global_load_lds_dwordx4 v186, s[0:1]
	s_add_i32 m0, s29, 0x12000
	s_nop 0
	global_load_lds_dwordx4 v128, s[0:1]
	v_readlane_b32 s0, v255, 45
	s_add_i32 m0, s29, 0x14000
	v_readlane_b32 s1, v255, 46
	s_nop 4
	global_load_lds_dwordx4 v186, s[0:1]
	s_add_i32 m0, s29, 0x16000
	s_cmp_eq_u32 s6, 1
	global_load_lds_dwordx4 v128, s[0:1]
	v_readlane_b32 s0, v255, 47
	s_mov_b32 m0, s29
	v_readlane_b32 s1, v255, 48
	s_nop 4
	global_load_lds_dwordx4 v132, s[0:1]
	s_mov_b32 m0, s30
	s_nop 0
	global_load_lds_dwordx4 v130, s[0:1]
	v_readlane_b32 s0, v255, 49
	s_mov_b32 m0, s31
	v_readlane_b32 s1, v255, 50
	s_nop 4
	global_load_lds_dwordx4 v132, s[0:1]
	s_mov_b32 m0, s34
	s_nop 0
	global_load_lds_dwordx4 v130, s[0:1]
	s_cselect_b64 s[0:1], -1, 0
	s_cmp_lg_u32 s6, 1
	s_cbranch_scc1 .LBB0_459
	s_barrier

; #define GEMMCALL if (0)
; #define FRESH_TID() asm volatile("" : "+v"(tid))
; __global__ void __launch_bounds__(NTHREADS, 2) mega(Params p) {
;     ...
;         {
;             for (int rep = 0; rep < REP_FOUR; ++rep) { FRESH_TID(); fft_phase(p, lds, tid); }
;             if (l == 0) {
;                 pg8::Gemm g{(const bf16_t*)(ws + WS_CTC), (const bf16_t*)(ws + WS_ZTC), 256, 2048, 512}; pg8::StaticOrder S; S.init(256, 2048, G, (int)blockIdx.x);
;                 EpiStore<0> E{MIX + (size_t)MX * KOUT + 512, KOUT, (size_t)256 * KOUT};
;                 GEMMCALL pg8::gemm_phase<EpiStore<0>, pg8::StaticOrder, true, true>(lds, g, S, E);
;             }
;             __syncthreads();
;             for (int rep = 0; rep < REP_ATTN; ++rep) { FRESH_TID(); attn_phase(p, l, lds, tid); }
;         }
.LBB0_491:
	s_cmp_lg_u32 s68, 1
	s_cbranch_scc1 .Lmix_done
	s_mov_b32 s68, 2
	s_waitcnt vmcnt(0) lgkmcnt(0)
	s_barrier
	v_readlane_b32 s12, v253, 29
	v_readlane_b32 s13, v253, 30
	v_readlane_b32 s28, v253, 31
	v_readlane_b32 s29, v253, 32
	v_readlane_b32 s40, v253, 19
	v_readlane_b32 s42, v253, 24
	v_readlane_b32 s43, v253, 25
	s_movk_i32 s46, 0x4000
	s_branch .Lmix_fft
